# KIND0 tile loop: LDS-DMA source addresses on the scalar side (running K/V pointers + two lane offsets) instead of eight 64-bit vector adds per tile
# speedup vs baseline: 1.0087x; 1.0087x over previous
; DI int otid() { int t = threadIdx.x; asm volatile("" : "+v"(t)); return t; }
; DI int crow(int reg, int h) { return (reg & 3) + 8 * (reg >> 2) + 4 * h; }
; template <int KIND>
; DI void attn_unit(const Params& p, int l, int b, int head, int qt, int qcol, int kcol, int vfeat, int gcol, int mixcol,
;                   int t1, int n1, int t2, int n2, char* smem) {
;     const int tid = otid(), lane = tid & 63, wave = tid >> 6, r = lane & 31, h = lane >> 5;
;     const int tq = qt * 128 + 32 * wave + r;
;     const size_t qrow = (size_t)b * TPB + tq;
;     const bf16_t* kbase = p.qkv + ((size_t)(kcol >> 6) * NTOK + (size_t)b * TPB) * 64;
;     const bf16_t* vbase = p.vT + ((size_t)b * 12 + (vfeat >> 6)) * 36 * 4096;
;     const int nt = n1 + n2;
;     bf16x8 qf[4];
;     {
;         const bf16_t* qp = p.qkv + ((size_t)(qcol >> 6) * NTOK + qrow) * 64 + 8 * h;
; #pragma unroll
;         for (int s = 0; s < 4; ++s) qf[s] = *(const bf16x8*)(qp + 16 * s);
;     }
;     int nrow = 0, r0w = 0, qc = 0, c0 = 0;
;     if (KIND == 2) {
;         nrow = 2 * qt + (wave >> 1); r0w = min(max(nrow - 4, 0), 24);
;         qc = 32 * (wave & 1) + r; c0 = min(max(qc - 8, 0), 48);
;         float* bias = (float*)(smem + ATT_BIAS);
;         for (int i = tid; i < 15 * 32; i += NTHREADS) { const int rr = i >> 5, cc = i & 31; bias[i] = cc < 31 ? p.rpb[((size_t)l * 6 + head) * 465 + rr * 31 + cc] * LOG2E : -INFINITY; }
;     }
;     int bcol[2][16];
;     if (KIND == 2) {
; #pragma unroll
;         for (int t = 0; t < 2; ++t)
; #pragma unroll
;             for (int e = 0; e < 16; ++e) {
;                 const int kc = 32 * t + crow(e, h);
;                 bcol[t][e] = ((unsigned)(kc - c0) < 16u) ? (kc - qc + 15) * 4 : 31 * 4;
;             }
;     }
;     f32x16 O0[2], O1[2];
; #pragma unroll
;     for (int t = 0; t < 2; ++t)
; #pragma unroll
;         for (int e = 0; e < 16; ++e) { O0[t][e] = 0.f; O1[t][e] = 0.f; }
;     float l0 = 0.f, l1 = 0.f;
;     const float zb = p.lam[8 + l * 4 + ((KIND == 1 && qcol >= 2048) ? 3 : KIND)];
;     f32x16 cz;
; #pragma unroll
;     for (int e = 0; e < 16; ++e) cz[e] = -zb;
;     const int kvoff = (8 * wave + (lane >> 3)) * 64 + (((lane & 7) ^ (((wave & 1) << 2) | (lane >> 4))) << 3);
;     const int xr = (r >> 1) & 7;
;     __syncthreads();
;     KV_ISSUE(t1, 0);
;     if (nt > 1) KV_ISSUE((1 < n1) ? t1 + 1 : t2 + (1 - n1), 1);
.LBB0_81:
	s_and_b32 s6, s8, 3
	s_mul_i32 s8, s6, 0x4800
	s_lshl_b32 s7, s7, 7
	s_mul_i32 s29, s35, 0x900
	s_add_i32 s5, s8, 0x12000
	s_mul_hi_i32 s9, s35, 0x900
	s_add_u32 s56, s29, s5
	s_mul_i32 s34, s35, 12
	v_mov_b32_e32 v23, v200
	s_addc_u32 s57, s9, 0
	s_mul_hi_i32 s5, s35, 12
	s_or_b32 s34, s34, s6
	s_load_dwordx4 s[40:43], s[0:1], 0xc0
	s_load_dwordx2 s[50:51], s[0:1], 0xf8
	v_ashrrev_i32_e32 v16, 6, v23
	s_mul_i32 s53, s34, 0x48000
	s_mul_hi_u32 s34, s34, 0x48000
	s_mul_i32 s5, s5, 0x48000
	v_and_b32_e32 v22, 31, v23
	v_lshl_add_u32 v0, v16, 5, s7
	s_lshl_b64 s[56:57], s[56:57], 7
	s_add_i32 s5, s34, s5
	v_or_b32_e32 v0, v0, v22
	s_add_u32 s58, s29, s8
	v_ashrrev_i32_e32 v1, 31, v0
	s_addc_u32 s59, s9, 0
	v_lshl_add_u64 v[0:1], s[58:59], 0, v[0:1]
	s_waitcnt lgkmcnt(0)
	s_add_u32 s58, s40, s56
	v_bfe_u32 v214, v23, 5, 1
	v_lshlrev_b64 v[0:1], 7, v[0:1]
	s_addc_u32 s59, s41, s57
	s_lshl_b64 s[56:57], s[48:49], 2
	v_lshl_add_u64 v[0:1], s[40:41], 0, v[0:1]
	v_lshlrev_b32_e32 v192, 4, v214
	s_add_u32 s56, s50, s56
	v_lshl_add_u64 v[0:1], v[0:1], 0, v[192:193]
	s_addc_u32 s57, s51, s57
	global_load_dwordx4 v[152:155], v[0:1], off
	global_load_dwordx4 v[144:147], v[0:1], off offset:32
	global_load_dwordx4 v[156:159], v[0:1], off offset:64
	global_load_dwordx4 v[148:151], v[0:1], off offset:96
	v_lshlrev_b32_e32 v17, 9, v16
	global_load_dword v0, v193, s[56:57] offset:32
	v_lshlrev_b32_e32 v18, 3, v23
	s_movk_i32 s56, 0x1c0
	v_lshlrev_b32_e32 v16, 2, v16
	v_and_or_b32 v17, v18, s56, v17
	v_and_b32_e32 v18, 7, v23
	v_and_b32_e32 v16, 4, v16
	v_bfe_u32 v19, v23, 4, 2
	s_add_u32 s53, s42, s53
	v_bitop3_b32 v16, v16, v18, v19 bitop3:0x36
	s_addc_u32 s5, s43, s5
	v_lshl_or_b32 v16, v16, 3, v17
	s_lshl_b32 s4, s4, 13
	s_add_u32 s56, s58, s4
	v_ashrrev_i32_e32 v17, 31, v16
	s_addc_u32 s57, s59, 0
	v_lshlrev_b64 v[16:17], 1, v[16:17]
	v_lshl_add_u64 v[20:21], s[56:57], 0, v[16:17]
	s_add_u32 s56, s53, s4
	v_lshl_add_u32 v220, v23, 4, 32
	v_lshrrev_b32_e32 v28, 1, v23
	v_bfe_u32 v29, v23, 1, 3
	s_addc_u32 s57, s5, 0
	v_readfirstlane_b32 s5, v220
	v_add_u32_e32 v23, 0x1000, v220
	s_mov_b32 m0, s5
	v_readfirstlane_b32 s5, v23
	v_add_u32_e32 v23, 0x2000, v220
	s_barrier
	global_load_lds_dwordx4 v[20:21], off
	v_lshl_add_u64 v[24:25], v[20:21], 0, s[26:27]
	s_mov_b32 m0, s5
	v_readfirstlane_b32 s5, v23
	v_add_u32_e32 v23, 0x3000, v220
	v_lshl_add_u64 v[18:19], s[56:57], 0, v[16:17]
	global_load_lds_dwordx4 v[24:25], off
	s_mov_b32 m0, s5
	v_readfirstlane_b32 s5, v23
	v_add_u32_e32 v23, 0x4000, v220
	global_load_lds_dwordx4 v[18:19], off
	v_lshl_add_u64 v[24:25], v[18:19], 0, s[26:27]
	s_mov_b32 m0, s5
	v_readfirstlane_b32 s5, v23
	v_add_u32_e32 v23, 0x5000, v220
	global_load_lds_dwordx4 v[24:25], off
	v_lshl_add_u64 v[24:25], v[20:21], 0, s[16:17]
	s_mov_b32 m0, s5
	v_readfirstlane_b32 s5, v23
	global_load_lds_dwordx4 v[24:25], off
	v_lshl_add_u64 v[20:21], v[20:21], 0, s[90:91]
	s_mov_b32 m0, s5
	v_lshl_add_u64 v[26:27], v[18:19], 0, s[16:17]
	global_load_lds_dwordx4 v[20:21], off
	v_add_u32_e32 v20, 0x6000, v220
	v_lshl_add_u64 v[18:19], v[18:19], 0, s[90:91]
	v_readfirstlane_b32 s5, v20
	v_add_u32_e32 v20, 0x7000, v220
	s_mov_b32 m0, s5
	v_readfirstlane_b32 s5, v20
	global_load_lds_dwordx4 v[26:27], off
	s_mov_b32 m0, s5
	s_lshl_b32 s5, s52, 13
	global_load_lds_dwordx4 v[18:19], off
	s_add_u32 s52, s5, 0x2000
	s_mul_i32 s53, s35, 0x360000
	s_mul_i32 s56, s6, 0x48000
	s_mul_hi_i32 s5, s35, 0x360000
	s_add_u32 s53, s53, s56
	s_addc_u32 s5, s5, 0
	s_add_u32 s53, s53, s4
	s_addc_u32 s5, s5, 0
	s_add_u32 s42, s42, s53
	s_addc_u32 s43, s43, s5
	v_lshl_add_u64 v[196:197], s[42:43], 0, v[16:17]
	s_add_u32 s98, s42, 0x4000
	s_addc_u32 s99, s43, 0
	s_mul_i32 s5, s6, 0x240000
	s_mul_hi_i32 s42, s35, 0x48000
	s_mul_i32 s35, s35, 0x48000
	s_add_u32 s5, s5, s35
	s_addc_u32 s35, 0, s42
	s_add_u32 s4, s5, s4
	v_bitop3_b32 v18, v214, v28, 7 bitop3:0x78
	s_addc_u32 s5, s35, 0
	v_lshlrev_b32_e32 v219, 4, v18
	v_bitop3_b32 v18, v214, v29, 2 bitop3:0x36
	s_add_u32 s4, s40, s4
	v_lshlrev_b32_e32 v218, 4, v18
	v_bitop3_b32 v18, v214, v29, 4 bitop3:0x36
	s_addc_u32 s5, s41, s5
	s_waitcnt vmcnt(0)
	v_xor_b32_e32 v0, 0x80000000, v0
	v_lshlrev_b32_e32 v217, 7, v22
	v_lshlrev_b32_e32 v216, 4, v18
	v_bitop3_b32 v18, v214, v29, 6 bitop3:0x36
	v_lshl_add_u64 v[198:199], s[4:5], 0, v[16:17]
	s_add_u32 s62, s4, 0x904000
	s_addc_u32 s63, s5, 0
	v_mov_b32_e32 v226, v16
	v_add_u32_e32 v227, 0x1000, v16
	v_mov_b32_e32 v16, 0
	s_mov_b32 s34, 2
	v_mov_b32_e32 v1, v0
	v_mov_b32_e32 v2, v0
	v_mov_b32_e32 v3, v0
	v_mov_b32_e32 v4, v0
	v_mov_b32_e32 v5, v0
	v_mov_b32_e32 v6, v0
	v_mov_b32_e32 v7, v0
	v_mov_b32_e32 v8, v0
	v_mov_b32_e32 v9, v0
	v_mov_b32_e32 v10, v0
	v_mov_b32_e32 v11, v0
	v_mov_b32_e32 v12, v0
	v_mov_b32_e32 v13, v0
	v_mov_b32_e32 v14, v0
	v_mov_b32_e32 v15, v0
	v_lshlrev_b32_e32 v215, 4, v18
	v_add_u32_e32 v221, 32, v217
	s_mov_b32 s35, 0
	s_mov_b64 s[4:5], 0
	v_mov_b32_e32 v17, v16
	v_mov_b32_e32 v18, v16
	v_mov_b32_e32 v19, v16
	v_mov_b32_e32 v20, v16
	v_mov_b32_e32 v21, v16
	v_mov_b32_e32 v22, v16
	v_mov_b32_e32 v23, v16
	v_mov_b32_e32 v24, v16
	v_mov_b32_e32 v25, v16
	v_mov_b32_e32 v26, v16
	v_mov_b32_e32 v27, v16
	v_mov_b32_e32 v28, v16
	v_mov_b32_e32 v29, v16
	v_mov_b32_e32 v30, v16
	v_mov_b32_e32 v31, v16
	v_mov_b32_e32 v48, v16
	v_mov_b32_e32 v49, v16
	v_mov_b32_e32 v50, v16
	v_mov_b32_e32 v51, v16
	v_mov_b32_e32 v52, v16
	v_mov_b32_e32 v53, v16
	v_mov_b32_e32 v54, v16
	v_mov_b32_e32 v55, v16
	v_mov_b32_e32 v56, v16
	v_mov_b32_e32 v57, v16
	v_mov_b32_e32 v58, v16
	v_mov_b32_e32 v59, v16
	v_mov_b32_e32 v60, v16
	v_mov_b32_e32 v61, v16
	v_mov_b32_e32 v62, v16
; template <int KIND>
; DI void attn_unit(const Params& p, int l, int b, int head, int qt, int qcol, int kcol, int vfeat, int gcol, int mixcol,
;                   int t1, int n1, int t2, int n2, char* smem) {
;     ...
;     f32x16 O0[2], O1[2];
; #pragma unroll
;     for (int t = 0; t < 2; ++t)
; #pragma unroll
;         for (int e = 0; e < 16; ++e) { O0[t][e] = 0.f; O1[t][e] = 0.f; }
;     float l0 = 0.f, l1 = 0.f;
;     const float zb = p.lam[8 + l * 4 + ((KIND == 1 && qcol >= 2048) ? 3 : KIND)];
;     f32x16 cz;
; #pragma unroll
;     for (int e = 0; e < 16; ++e) cz[e] = -zb;
;     const int kvoff = (8 * wave + (lane >> 3)) * 64 + (((lane & 7) ^ (((wave & 1) << 2) | (lane >> 4))) << 3);
;     const int xr = (r >> 1) & 7;
;     __syncthreads();
;     KV_ISSUE(t1, 0);
;     if (nt > 1) KV_ISSUE((1 < n1) ? t1 + 1 : t2 + (1 - n1), 1);
;     int sc = 0, sn = 2;
;     for (int it = 0; it < nt; ++it) {
;         const int tile = (it < n1) ? t1 + it : t2 + (it - n1);
;         if (it + 1 < nt) asm volatile("s_waitcnt vmcnt(4)" ::: "memory"); else asm volatile("s_waitcnt vmcnt(0)" ::: "memory");
;         __builtin_amdgcn_s_barrier();
;         const char* sk = smem + sc * ATT_SLOT;
;         const char* sv = sk + ATT_V;
;         bool active = true;
;         if (KIND == 2 && tile < 32) active = (tile >= r0w) && (tile < r0w + 8);
;         bf16x8 kf[8], vf[8];
;         if (active) {
; #pragma unroll
;             for (int s = 0; s < 4; ++s)
; #pragma unroll
;                 for (int t = 0; t < 2; ++t) kf[2 * s + t] = *(const bf16x8*)(sk + (32 * t + r) * 128 + (((2 * s + h) ^ xr) << 4));
;         }
;         __builtin_amdgcn_sched_barrier(0);
;         if (it + 2 < nt) { const int nx = (it + 2 < n1) ? t1 + it + 2 : t2 + (it + 2 - n1); KV_ISSUE(nx, sn); }
;         sc = (sc == 2) ? 0 : sc + 1; sn = (sn == 2) ? 0 : sn + 1;
;         __builtin_amdgcn_sched_barrier(0);
;         if (active) {
;     ...
;             if (KIND == 0) {
;                 f32x16 S0[2], S1[2];
; #pragma unroll
;                 for (int t = 0; t < 2; ++t) { S0[t] = MFMA(kf[t], qf[0], cz); S1[t] = MFMA(kf[4 + t], qf[2], cz); }
; #pragma unroll
;                 for (int t = 0; t < 2; ++t) { S0[t] = MFMA(kf[2 + t], qf[1], S0[t]); S1[t] = MFMA(kf[6 + t], qf[3], S1[t]); }
;                 LOAD_VF();
;                 softmax_tile(S0, l0);
;                 pv_tile(S0, O0, vf);
	v_mov_b32_e32 v63, v16
	v_mov_b32_e32 v32, v16
	v_mov_b32_e32 v33, v16
	v_mov_b32_e32 v34, v16
	v_mov_b32_e32 v35, v16
	v_mov_b32_e32 v36, v16
	v_mov_b32_e32 v37, v16
	v_mov_b32_e32 v38, v16
	v_mov_b32_e32 v39, v16
	v_mov_b32_e32 v40, v16
	v_mov_b32_e32 v41, v16
	v_mov_b32_e32 v42, v16
	v_mov_b32_e32 v43, v16
	v_mov_b32_e32 v44, v16
	v_mov_b32_e32 v45, v16
	v_mov_b32_e32 v46, v16
	v_mov_b32_e32 v47, v16
	v_mov_b32_e32 v64, v16
	v_mov_b32_e32 v65, v16
	v_mov_b32_e32 v66, v16
	v_mov_b32_e32 v67, v16
	v_mov_b32_e32 v68, v16
	v_mov_b32_e32 v69, v16
	v_mov_b32_e32 v70, v16
	v_mov_b32_e32 v71, v16
	v_mov_b32_e32 v72, v16
	v_mov_b32_e32 v73, v16
	v_mov_b32_e32 v74, v16
	v_mov_b32_e32 v75, v16
	v_mov_b32_e32 v76, v16
	v_mov_b32_e32 v77, v16
	v_mov_b32_e32 v78, v16
	v_mov_b32_e32 v79, v16
	v_mov_b32_e32 v194, v16
	v_mov_b32_e32 v195, v16
	v_readfirstlane_b32 s100, v220
	v_mov_b32_e32 v80, 0
	v_mov_b32_e32 v81, 0
	v_mov_b32_e32 v82, 0
	v_mov_b32_e32 v83, 0
	v_mov_b32_e32 v84, 0
	v_mov_b32_e32 v85, 0
	v_mov_b32_e32 v86, 0
	v_mov_b32_e32 v87, 0
	v_mov_b32_e32 v88, 0
	v_mov_b32_e32 v89, 0
	v_mov_b32_e32 v90, 0
	v_mov_b32_e32 v91, 0
	v_mov_b32_e32 v92, 0
	v_mov_b32_e32 v93, 0
	v_mov_b32_e32 v94, 0
	v_mov_b32_e32 v95, 0
	v_mov_b32_e32 v96, 0
	v_mov_b32_e32 v97, 0
	v_mov_b32_e32 v98, 0
	v_mov_b32_e32 v99, 0
	v_mov_b32_e32 v100, 0
	v_mov_b32_e32 v101, 0
	v_mov_b32_e32 v102, 0
	v_mov_b32_e32 v103, 0
	v_mov_b32_e32 v104, 0
	v_mov_b32_e32 v105, 0
	v_mov_b32_e32 v106, 0
	v_mov_b32_e32 v107, 0
	v_mov_b32_e32 v108, 0
	v_mov_b32_e32 v109, 0
	v_mov_b32_e32 v110, 0
	v_mov_b32_e32 v111, 0
	v_mov_b32_e32 v160, 0
	v_mov_b32_e32 v161, 0
	v_mov_b32_e32 v162, 0
	v_mov_b32_e32 v163, 0
	v_mov_b32_e32 v164, 0
	v_mov_b32_e32 v165, 0
	v_mov_b32_e32 v166, 0
	v_mov_b32_e32 v167, 0
	v_mov_b32_e32 v168, 0
	v_mov_b32_e32 v169, 0
	v_mov_b32_e32 v170, 0
	v_mov_b32_e32 v171, 0
	v_mov_b32_e32 v172, 0
	v_mov_b32_e32 v173, 0
	v_mov_b32_e32 v174, 0
	v_mov_b32_e32 v175, 0
	v_mov_b32_e32 v176, 0
	v_mov_b32_e32 v177, 0
	v_mov_b32_e32 v178, 0
	v_mov_b32_e32 v179, 0
	v_mov_b32_e32 v180, 0
	v_mov_b32_e32 v181, 0
	v_mov_b32_e32 v182, 0
	v_mov_b32_e32 v183, 0
	v_mov_b32_e32 v184, 0
	v_mov_b32_e32 v185, 0
	v_mov_b32_e32 v186, 0
	v_mov_b32_e32 v187, 0
	v_mov_b32_e32 v188, 0
	v_mov_b32_e32 v189, 0
	v_mov_b32_e32 v190, 0
	v_mov_b32_e32 v191, 0
	v_mov_b32_e32 v252, 0
	v_mov_b32_e32 v253, 0
.LBB0_82:
	v_lshl_add_u32 v225, s35, 14, v221
	v_add_u32_e32 v222, v225, v218
	v_add_u32_e32 v223, v225, v216
	v_add_u32_e32 v224, v225, v215
	v_add_u32_e32 v225, v225, v219
	s_waitcnt vmcnt(4)
	s_barrier
	ds_read_b128 v[234:237], v225
	ds_read_b128 v[238:241], v225 offset:4096
	ds_read_b128 v[242:245], v222
	ds_read_b128 v[246:249], v222 offset:4096
	s_lshl_b32 s101, s34, 14
	s_add_i32 s101, s101, s100
	s_add_i32 s42, s35, 1
	s_cmp_lg_u32 s35, 2
	s_cselect_b32 s35, s42, 0
	s_add_i32 s42, s34, 1
	v_add_f32_e32 v252, v80, v252
	v_add_f32_e32 v253, v81, v253
	v_cvt_pk_bf16_f32 v80, v80, v81
	v_add_f32_e32 v252, v82, v252
	v_add_f32_e32 v253, v83, v253
	v_cvt_pk_bf16_f32 v81, v82, v83
	v_add_f32_e32 v252, v84, v252
	v_add_f32_e32 v253, v85, v253
	v_cvt_pk_bf16_f32 v82, v84, v85
	v_add_f32_e32 v252, v86, v252
	v_add_f32_e32 v253, v87, v253
	v_cvt_pk_bf16_f32 v83, v86, v87
	s_mov_b32 m0, s101
	s_waitcnt lgkmcnt(0)
	v_mfma_f32_32x32x16_bf16 v[128:143], v[234:237], v[152:155], v[0:15]
	global_load_lds_dwordx4 v226, s[62:63]
	s_add_u32 m0, s101, 0x1000
	v_add_f32_e32 v252, v88, v252
	v_add_f32_e32 v253, v89, v253
	v_cvt_pk_bf16_f32 v88, v88, v89
	v_mfma_f32_32x32x16_bf16 v[112:127], v[238:241], v[152:155], v[0:15]
	global_load_lds_dwordx4 v227, s[62:63]
	s_add_u32 m0, s101, 0x2000
	v_add_f32_e32 v252, v90, v252
	v_add_f32_e32 v253, v91, v253
	v_cvt_pk_bf16_f32 v89, v90, v91
	v_mfma_f32_32x32x16_bf16 v[128:143], v[242:245], v[144:147], v[128:143]
	global_load_lds_dwordx4 v226, s[98:99]
	s_add_u32 m0, s101, 0x3000
	v_add_f32_e32 v252, v92, v252
	v_add_f32_e32 v253, v93, v253
	v_cvt_pk_bf16_f32 v90, v92, v93
	v_mfma_f32_32x32x16_bf16 v[112:127], v[246:249], v[144:147], v[112:127]
	global_load_lds_dwordx4 v227, s[98:99]
	v_add_f32_e32 v252, v94, v252
	v_add_f32_e32 v253, v95, v253
	v_cvt_pk_bf16_f32 v91, v94, v95
	v_add_f32_e32 v252, v252, v253
	v_add_f32_e32 v194, v194, v252
	s_cmp_lg_u32 s34, 2
	s_cselect_b32 s34, s42, 0
	s_add_u32 s62, s62, 0x2000
	s_addc_u32 s63, s63, 0
	s_add_u32 s98, s98, 0x2000
	s_addc_u32 s99, s99, 0
	ds_read_b128 v[234:237], v223
	ds_read_b128 v[238:241], v223 offset:4096
	ds_read_b128 v[242:245], v224
	ds_read_b128 v[246:249], v224 offset:4096
	v_mfma_f32_32x32x16_bf16 v[64:79], v[188:191], v[96:99], v[64:79]
	v_exp_f32_e32 v128, v128
	v_exp_f32_e32 v129, v129
	v_exp_f32_e32 v130, v130
	v_exp_f32_e32 v131, v131
	v_mfma_f32_32x32x16_bf16 v[16:31], v[184:187], v[96:99], v[16:31]
	v_exp_f32_e32 v132, v132
	v_exp_f32_e32 v133, v133
	v_exp_f32_e32 v134, v134
	v_exp_f32_e32 v135, v135
	v_mfma_f32_32x32x16_bf16 v[64:79], v[180:183], v[104:107], v[64:79]
	v_exp_f32_e32 v136, v136
	v_exp_f32_e32 v137, v137
	v_exp_f32_e32 v138, v138
	v_exp_f32_e32 v139, v139
	v_add_f32_e64 v250, v128, 0
	v_add_f32_e64 v251, v129, 0
	v_cvt_pk_bf16_f32 v128, v128, v129
	v_add_f32_e32 v250, v130, v250
	v_add_f32_e32 v251, v131, v251
	v_cvt_pk_bf16_f32 v129, v130, v131
	v_mfma_f32_32x32x16_bf16 v[16:31], v[176:179], v[104:107], v[16:31]
	v_exp_f32_e32 v140, v140
	v_exp_f32_e32 v141, v141
	v_exp_f32_e32 v142, v142
	v_exp_f32_e32 v143, v143
	v_add_f32_e32 v250, v132, v250
	v_add_f32_e32 v251, v133, v251
	v_cvt_pk_bf16_f32 v130, v132, v133
	v_add_f32_e32 v250, v134, v250
	v_add_f32_e32 v251, v135, v251
	v_cvt_pk_bf16_f32 v131, v134, v135
	v_mfma_f32_32x32x16_bf16 v[64:79], v[172:175], v[80:83], v[64:79]
	v_exp_f32_e32 v112, v112
	v_exp_f32_e32 v113, v113
	v_exp_f32_e32 v114, v114
	v_exp_f32_e32 v115, v115
	v_add_f32_e32 v250, v136, v250
	v_add_f32_e32 v251, v137, v251
	v_cvt_pk_bf16_f32 v136, v136, v137
	v_add_f32_e32 v250, v138, v250
	v_add_f32_e32 v251, v139, v251
	v_cvt_pk_bf16_f32 v137, v138, v139
	v_mfma_f32_32x32x16_bf16 v[16:31], v[168:171], v[80:83], v[16:31]
	v_exp_f32_e32 v116, v116
	v_exp_f32_e32 v117, v117
	v_exp_f32_e32 v118, v118
	v_exp_f32_e32 v119, v119
	v_add_f32_e32 v250, v140, v250
	v_add_f32_e32 v251, v141, v251
	v_cvt_pk_bf16_f32 v138, v140, v141
	v_add_f32_e32 v250, v142, v250
	v_add_f32_e32 v251, v143, v251
	v_cvt_pk_bf16_f32 v139, v142, v143
	v_mfma_f32_32x32x16_bf16 v[64:79], v[164:167], v[88:91], v[64:79]
	v_exp_f32_e32 v120, v120
	v_exp_f32_e32 v121, v121
	v_exp_f32_e32 v122, v122
	v_exp_f32_e32 v123, v123
	v_mfma_f32_32x32x16_bf16 v[16:31], v[160:163], v[88:91], v[16:31]
	v_exp_f32_e32 v124, v124
	v_exp_f32_e32 v125, v125
	v_exp_f32_e32 v126, v126
	v_exp_f32_e32 v127, v127
	s_waitcnt lgkmcnt(0)
; #define MFMA(a, b, c) __builtin_amdgcn_mfma_f32_32x32x16_bf16((a), (b), (c), 0, 0, 0)
; #define KV_ISSUE(tile_, slot_) do { \
;     const bf16_t* kp_ = kbase + (size_t)(tile_) * 4096 + kvoff; const bf16_t* vp_ = vbase + (size_t)(tile_) * 4096 + kvoff; \
;     char* lp_ = smem + (slot_) * ATT_SLOT + tid * 16; \
;     dma16(kp_, lp_); dma16(kp_ + 2048, lp_ + 4096); dma16(vp_, lp_ + ATT_V); dma16(vp_ + 2048, lp_ + ATT_V + 4096); } while (0)
; template <int KIND>
; DI void attn_unit(const Params& p, int l, int b, int head, int qt, int qcol, int kcol, int vfeat, int gcol, int mixcol,
;                   int t1, int n1, int t2, int n2, char* smem) {
;     ...
;     for (int it = 0; it < nt; ++it) {
;         const int tile = (it < n1) ? t1 + it : t2 + (it - n1);
;         if (it + 1 < nt) asm volatile("s_waitcnt vmcnt(4)" ::: "memory"); else asm volatile("s_waitcnt vmcnt(0)" ::: "memory");
;         __builtin_amdgcn_s_barrier();
;         const char* sk = smem + sc * ATT_SLOT;
;         const char* sv = sk + ATT_V;
;         bool active = true;
;         if (KIND == 2 && tile < 32) active = (tile >= r0w) && (tile < r0w + 8);
;         bf16x8 kf[8], vf[8];
;         if (active) {
; #pragma unroll
;             for (int s = 0; s < 4; ++s)
; #pragma unroll
;                 for (int t = 0; t < 2; ++t) kf[2 * s + t] = *(const bf16x8*)(sk + (32 * t + r) * 128 + (((2 * s + h) ^ xr) << 4));
;         }
;         __builtin_amdgcn_sched_barrier(0);
;         if (it + 2 < nt) { const int nx = (it + 2 < n1) ? t1 + it + 2 : t2 + (it + 2 - n1); KV_ISSUE(nx, sn); }
;         sc = (sc == 2) ? 0 : sc + 1; sn = (sn == 2) ? 0 : sn + 1;
;         __builtin_amdgcn_sched_barrier(0);
;         if (active) {
;     ...
;             if (KIND == 0) {
;                 f32x16 S0[2], S1[2];
; #pragma unroll
;                 for (int t = 0; t < 2; ++t) { S0[t] = MFMA(kf[t], qf[0], cz); S1[t] = MFMA(kf[4 + t], qf[2], cz); }
; #pragma unroll
;                 for (int t = 0; t < 2; ++t) { S0[t] = MFMA(kf[2 + t], qf[1], S0[t]); S1[t] = MFMA(kf[6 + t], qf[3], S1[t]); }
;                 LOAD_VF();
;                 softmax_tile(S0, l0);
;                 pv_tile(S0, O0, vf);
;                 softmax_tile(S1, l1);
;                 pv_tile(S1, O1, vf);
	ds_read_b128 v[188:191], v225 offset:8192
	ds_read_b128 v[184:187], v225 offset:12288
	ds_read_b128 v[180:183], v222 offset:8192
	ds_read_b128 v[176:179], v222 offset:12288
	ds_read_b128 v[172:175], v223 offset:8192
	ds_read_b128 v[168:171], v223 offset:12288
	ds_read_b128 v[164:167], v224 offset:8192
	ds_read_b128 v[160:163], v224 offset:12288
	v_mfma_f32_32x32x16_bf16 v[96:111], v[234:237], v[156:159], v[0:15]
	v_add_f32_e32 v250, v112, v250
	v_add_f32_e32 v251, v113, v251
	v_cvt_pk_bf16_f32 v112, v112, v113
	v_add_f32_e32 v250, v114, v250
	v_add_f32_e32 v251, v115, v251
	v_cvt_pk_bf16_f32 v113, v114, v115
	v_mfma_f32_32x32x16_bf16 v[80:95], v[238:241], v[156:159], v[0:15]
	v_add_f32_e32 v250, v116, v250
	v_add_f32_e32 v251, v117, v251
	v_cvt_pk_bf16_f32 v114, v116, v117
	v_add_f32_e32 v250, v118, v250
	v_add_f32_e32 v251, v119, v251
	v_cvt_pk_bf16_f32 v115, v118, v119
	v_mfma_f32_32x32x16_bf16 v[96:111], v[242:245], v[148:151], v[96:111]
	v_add_f32_e32 v250, v120, v250
	v_add_f32_e32 v251, v121, v251
	v_cvt_pk_bf16_f32 v120, v120, v121
	v_add_f32_e32 v250, v122, v250
	v_add_f32_e32 v251, v123, v251
	v_cvt_pk_bf16_f32 v121, v122, v123
	v_mfma_f32_32x32x16_bf16 v[80:95], v[246:249], v[148:151], v[80:95]
	v_add_f32_e32 v250, v124, v250
	v_add_f32_e32 v251, v125, v251
	v_cvt_pk_bf16_f32 v122, v124, v125
	v_add_f32_e32 v250, v126, v250
	v_add_f32_e32 v251, v127, v251
	v_cvt_pk_bf16_f32 v123, v126, v127
	v_add_f32_e32 v250, v250, v251
	v_add_f32_e32 v195, v195, v250
	s_add_u32 s4, s4, 0x2000
	s_addc_u32 s5, s5, 0
	s_waitcnt lgkmcnt(0)
	v_mfma_f32_32x32x16_bf16 v[48:63], v[188:191], v[128:131], v[48:63]
	v_exp_f32_e32 v96, v96
	v_exp_f32_e32 v97, v97
	v_exp_f32_e32 v98, v98
	v_exp_f32_e32 v99, v99
	v_mfma_f32_32x32x16_bf16 v[32:47], v[184:187], v[128:131], v[32:47]
	v_exp_f32_e32 v100, v100
	v_exp_f32_e32 v101, v101
	v_exp_f32_e32 v102, v102
	v_exp_f32_e32 v103, v103
	v_mfma_f32_32x32x16_bf16 v[48:63], v[180:183], v[136:139], v[48:63]
	v_exp_f32_e32 v104, v104
	v_exp_f32_e32 v105, v105
	v_exp_f32_e32 v106, v106
	v_exp_f32_e32 v107, v107
	v_add_f32_e64 v252, v96, 0
	v_add_f32_e64 v253, v97, 0
	v_cvt_pk_bf16_f32 v96, v96, v97
	v_add_f32_e32 v252, v98, v252
	v_add_f32_e32 v253, v99, v253
	v_cvt_pk_bf16_f32 v97, v98, v99
	v_mfma_f32_32x32x16_bf16 v[32:47], v[176:179], v[136:139], v[32:47]
	v_exp_f32_e32 v108, v108
	v_exp_f32_e32 v109, v109
	v_exp_f32_e32 v110, v110
	v_exp_f32_e32 v111, v111
	v_add_f32_e32 v252, v100, v252
	v_add_f32_e32 v253, v101, v253
	v_cvt_pk_bf16_f32 v98, v100, v101
	v_add_f32_e32 v252, v102, v252
	v_add_f32_e32 v253, v103, v253
	v_cvt_pk_bf16_f32 v99, v102, v103
	v_mfma_f32_32x32x16_bf16 v[48:63], v[172:175], v[112:115], v[48:63]
	v_exp_f32_e32 v80, v80
	v_exp_f32_e32 v81, v81
	v_exp_f32_e32 v82, v82
	v_exp_f32_e32 v83, v83
	v_add_f32_e32 v252, v104, v252
	v_add_f32_e32 v253, v105, v253
	v_cvt_pk_bf16_f32 v104, v104, v105
	v_add_f32_e32 v252, v106, v252
	v_add_f32_e32 v253, v107, v253
	v_cvt_pk_bf16_f32 v105, v106, v107
	v_mfma_f32_32x32x16_bf16 v[32:47], v[168:171], v[112:115], v[32:47]
	v_exp_f32_e32 v84, v84
	v_exp_f32_e32 v85, v85
	v_exp_f32_e32 v86, v86
	v_exp_f32_e32 v87, v87
	v_add_f32_e32 v252, v108, v252
	v_add_f32_e32 v253, v109, v253
	v_cvt_pk_bf16_f32 v106, v108, v109
	v_add_f32_e32 v252, v110, v252
	v_add_f32_e32 v253, v111, v253
	v_cvt_pk_bf16_f32 v107, v110, v111
	v_mfma_f32_32x32x16_bf16 v[48:63], v[164:167], v[120:123], v[48:63]
	v_exp_f32_e32 v88, v88
	v_exp_f32_e32 v89, v89
	v_exp_f32_e32 v90, v90
	v_exp_f32_e32 v91, v91
	v_mfma_f32_32x32x16_bf16 v[32:47], v[160:163], v[120:123], v[32:47]
	v_exp_f32_e32 v92, v92
	v_exp_f32_e32 v93, v93
	v_exp_f32_e32 v94, v94
	v_exp_f32_e32 v95, v95
	s_cmp_eq_u32 s52, s4
	s_cbranch_scc0 .LBB0_82
	v_add_f32_e32 v252, v80, v252
	v_add_f32_e32 v253, v81, v253
	v_cvt_pk_bf16_f32 v80, v80, v81
	v_add_f32_e32 v252, v82, v252
	v_add_f32_e32 v253, v83, v253
	v_cvt_pk_bf16_f32 v81, v82, v83
	v_add_f32_e32 v252, v84, v252
	v_add_f32_e32 v253, v85, v253
	v_cvt_pk_bf16_f32 v82, v84, v85
	v_add_f32_e32 v252, v86, v252
	v_add_f32_e32 v253, v87, v253
	v_cvt_pk_bf16_f32 v83, v86, v87
	v_add_f32_e32 v252, v88, v252
	v_add_f32_e32 v253, v89, v253
	v_cvt_pk_bf16_f32 v88, v88, v89
	v_add_f32_e32 v252, v90, v252
	v_add_f32_e32 v253, v91, v253
	v_cvt_pk_bf16_f32 v89, v90, v91
	v_add_f32_e32 v252, v92, v252
	v_add_f32_e32 v253, v93, v253
	v_cvt_pk_bf16_f32 v90, v92, v93
	v_add_f32_e32 v252, v94, v252
	v_add_f32_e32 v253, v95, v253
	v_cvt_pk_bf16_f32 v91, v94, v95
	v_add_f32_e32 v252, v252, v253
	v_add_f32_e32 v194, v194, v252
	v_mfma_f32_32x32x16_bf16 v[64:79], v[188:191], v[96:99], v[64:79]
	v_mfma_f32_32x32x16_bf16 v[16:31], v[184:187], v[96:99], v[16:31]
	v_mfma_f32_32x32x16_bf16 v[64:79], v[180:183], v[104:107], v[64:79]
	v_mfma_f32_32x32x16_bf16 v[16:31], v[176:179], v[104:107], v[16:31]
	v_mfma_f32_32x32x16_bf16 v[64:79], v[172:175], v[80:83], v[64:79]
	v_mfma_f32_32x32x16_bf16 v[16:31], v[168:171], v[80:83], v[16:31]
	v_mfma_f32_32x32x16_bf16 v[64:79], v[164:167], v[88:91], v[64:79]
	v_mfma_f32_32x32x16_bf16 v[16:31], v[160:163], v[88:91], v[16:31]
	s_lshl_b32 s4, s35, 14
	s_add_i32 s5, s4, 32
	v_add_u32_e32 v92, s5, v217
	v_add_u32_e32 v180, v92, v219
	v_add_u32_e32 v196, v92, v218
	v_add_u32_e32 v197, v92, v216
	v_add_u32_e32 v198, v92, v215
	s_waitcnt vmcnt(4)
	s_barrier
; #define MFMA(a, b, c) __builtin_amdgcn_mfma_f32_32x32x16_bf16((a), (b), (c), 0, 0, 0)
; #define KV_ISSUE(tile_, slot_) do { \
;     const bf16_t* kp_ = kbase + (size_t)(tile_) * 4096 + kvoff; const bf16_t* vp_ = vbase + (size_t)(tile_) * 4096 + kvoff; \
;     char* lp_ = smem + (slot_) * ATT_SLOT + tid * 16; \
;     dma16(kp_, lp_); dma16(kp_ + 2048, lp_ + 4096); dma16(vp_, lp_ + ATT_V); dma16(vp_ + 2048, lp_ + ATT_V + 4096); } while (0)
; template <int KIND>
; DI void attn_unit(const Params& p, int l, int b, int head, int qt, int qcol, int kcol, int vfeat, int gcol, int mixcol,
;                   int t1, int n1, int t2, int n2, char* smem) {
;     ...
;     for (int it = 0; it < nt; ++it) {
;         const int tile = (it < n1) ? t1 + it : t2 + (it - n1);
;         if (it + 1 < nt) asm volatile("s_waitcnt vmcnt(4)" ::: "memory"); else asm volatile("s_waitcnt vmcnt(0)" ::: "memory");
;         __builtin_amdgcn_s_barrier();
;         const char* sk = smem + sc * ATT_SLOT;
;         const char* sv = sk + ATT_V;
;         bool active = true;
;         if (KIND == 2 && tile < 32) active = (tile >= r0w) && (tile < r0w + 8);
;         bf16x8 kf[8], vf[8];
;         if (active) {
; #pragma unroll
;             for (int s = 0; s < 4; ++s)
; #pragma unroll
;                 for (int t = 0; t < 2; ++t) kf[2 * s + t] = *(const bf16x8*)(sk + (32 * t + r) * 128 + (((2 * s + h) ^ xr) << 4));
;         }
;         __builtin_amdgcn_sched_barrier(0);
;         if (it + 2 < nt) { const int nx = (it + 2 < n1) ? t1 + it + 2 : t2 + (it + 2 - n1); KV_ISSUE(nx, sn); }
;         sc = (sc == 2) ? 0 : sc + 1; sn = (sn == 2) ? 0 : sn + 1;
;         __builtin_amdgcn_sched_barrier(0);
;         if (active) {
;     ...
;             if (KIND == 0) {
;                 f32x16 S0[2], S1[2];
; #pragma unroll
;                 for (int t = 0; t < 2; ++t) { S0[t] = MFMA(kf[t], qf[0], cz); S1[t] = MFMA(kf[4 + t], qf[2], cz); }
; #pragma unroll
;                 for (int t = 0; t < 2; ++t) { S0[t] = MFMA(kf[2 + t], qf[1], S0[t]); S1[t] = MFMA(kf[6 + t], qf[3], S1[t]); }
;                 LOAD_VF();
;                 softmax_tile(S0, l0);
;                 pv_tile(S0, O0, vf);
;                 softmax_tile(S1, l1);
;                 pv_tile(S1, O1, vf);
	ds_read_b128 v[80:83], v180
	ds_read_b128 v[84:87], v180 offset:4096
	ds_read_b128 v[160:163], v196
	ds_read_b128 v[164:167], v196 offset:4096
	ds_read_b128 v[88:91], v197
	ds_read_b128 v[168:171], v197 offset:4096
	ds_read_b128 v[172:175], v198
	ds_read_b128 v[176:179], v198 offset:4096
	s_waitcnt lgkmcnt(0)
	v_mfma_f32_32x32x16_bf16 v[128:143], v[80:83], v[152:155], v[0:15]
	v_mfma_f32_32x32x16_bf16 v[96:111], v[88:91], v[156:159], v[0:15]
	v_mfma_f32_32x32x16_bf16 v[112:127], v[84:87], v[152:155], v[0:15]
	v_mfma_f32_32x32x16_bf16 v[80:95], v[168:171], v[156:159], v[0:15]
	v_mfma_f32_32x32x16_bf16 v[128:143], v[160:163], v[144:147], v[128:143]
	v_mfma_f32_32x32x16_bf16 v[96:111], v[172:175], v[148:151], v[96:111]
	v_mfma_f32_32x32x16_bf16 v[112:127], v[164:167], v[144:147], v[112:127]
	v_mfma_f32_32x32x16_bf16 v[80:95], v[176:179], v[148:151], v[80:95]
	ds_read_b128 v[188:191], v180 offset:8192
	ds_read_b128 v[184:187], v180 offset:12288
	ds_read_b128 v[180:183], v196 offset:8192
	ds_read_b128 v[176:179], v196 offset:12288
	ds_read_b128 v[172:175], v197 offset:8192
	ds_read_b128 v[168:171], v197 offset:12288
	ds_read_b128 v[164:167], v198 offset:8192
	ds_read_b128 v[160:163], v198 offset:12288
	s_nop 0
	v_exp_f32_e32 v128, v128
	v_exp_f32_e32 v129, v129
	v_exp_f32_e32 v130, v130
	v_exp_f32_e32 v131, v131
	v_exp_f32_e32 v132, v132
	v_exp_f32_e32 v133, v133
	v_exp_f32_e32 v134, v134
	v_exp_f32_e32 v135, v135
	v_add_f32_e64 v196, v128, 0
	v_add_f32_e64 v197, v129, 0
	v_cvt_pk_bf16_f32 v128, v128, v129
	v_add_f32_e64 v196, v130, v196
	v_add_f32_e64 v197, v131, v197
	v_cvt_pk_bf16_f32 v129, v130, v131
	v_cvt_pk_bf16_f32 v130, v132, v133
	v_cvt_pk_bf16_f32 v131, v134, v135
	v_add_f32_e64 v196, v132, v196
	v_add_f32_e64 v197, v133, v197
	v_exp_f32_e32 v136, v136
	s_waitcnt lgkmcnt(0)
	v_mfma_f32_32x32x16_bf16 v[48:63], v[188:191], v[128:131], v[48:63]
	v_exp_f32_e32 v137, v137
	v_exp_f32_e32 v138, v138
	v_exp_f32_e32 v139, v139
	v_exp_f32_e32 v132, v140
	v_exp_f32_e32 v133, v141
	v_exp_f32_e32 v140, v142
	v_exp_f32_e32 v141, v143
	v_mfma_f32_32x32x16_bf16 v[32:47], v[184:187], v[128:131], v[32:47]
	v_add_f32_e64 v134, v134, v196
	v_add_f32_e64 v135, v135, v197
	v_cvt_pk_bf16_f32 v128, v136, v137
	v_cvt_pk_bf16_f32 v129, v138, v139
	v_cvt_pk_bf16_f32 v130, v132, v133
	v_cvt_pk_bf16_f32 v131, v140, v141
	v_add_f32_e64 v134, v136, v134
	v_add_f32_e64 v135, v137, v135
	v_exp_f32_e32 v112, v112
	v_mfma_f32_32x32x16_bf16 v[48:63], v[180:183], v[128:131], v[48:63]
	v_add_f32_e64 v134, v138, v134
	v_add_f32_e64 v135, v139, v135
	v_exp_f32_e32 v113, v113
	v_add_f32_e64 v134, v132, v134
	v_add_f32_e64 v135, v133, v135
	v_exp_f32_e32 v116, v116
	v_add_f32_e64 v132, v140, v134
	v_add_f32_e64 v133, v141, v135
	v_exp_f32_e32 v134, v114
	v_exp_f32_e32 v135, v115
	v_mfma_f32_32x32x16_bf16 v[32:47], v[176:179], v[128:131], v[32:47]
	v_exp_f32_e32 v117, v117
	v_exp_f32_e32 v118, v118
	v_exp_f32_e32 v119, v119
	v_add_f32_e64 v132, v112, v132
	v_add_f32_e64 v133, v113, v133
	v_cvt_pk_bf16_f32 v112, v112, v113
	v_cvt_pk_bf16_f32 v113, v134, v135
	v_cvt_pk_bf16_f32 v114, v116, v117
	v_cvt_pk_bf16_f32 v115, v118, v119
	v_add_f32_e64 v128, v134, v132
	v_add_f32_e64 v129, v135, v133
	v_exp_f32_e32 v120, v120
	v_mfma_f32_32x32x16_bf16 v[48:63], v[172:175], v[112:115], v[48:63]
	v_add_f32_e64 v116, v116, v128
	v_add_f32_e64 v117, v117, v129
	v_exp_f32_e32 v121, v121
	v_add_f32_e64 v116, v118, v116
	v_add_f32_e64 v117, v119, v117
	v_exp_f32_e32 v118, v122
	v_exp_f32_e32 v119, v123
	v_exp_f32_e32 v122, v124
	v_exp_f32_e32 v123, v125
	v_mfma_f32_32x32x16_bf16 v[32:47], v[168:171], v[112:115], v[32:47]
	v_exp_f32_e32 v124, v126
	v_exp_f32_e32 v125, v127
	v_exp_f32_e32 v96, v96
	v_exp_f32_e32 v97, v97
	v_exp_f32_e32 v98, v98
	v_exp_f32_e32 v99, v99
	v_exp_f32_e32 v100, v100
	v_exp_f32_e32 v101, v101
	v_exp_f32_e32 v102, v102
	v_exp_f32_e32 v103, v103
	v_cvt_pk_bf16_f32 v112, v120, v121
	v_cvt_pk_bf16_f32 v113, v118, v119
	v_cvt_pk_bf16_f32 v114, v122, v123
	v_cvt_pk_bf16_f32 v115, v124, v125
	v_exp_f32_e32 v104, v104
	v_exp_f32_e32 v105, v105
	v_mfma_f32_32x32x16_bf16 v[48:63], v[164:167], v[112:115], v[48:63]
	v_exp_f32_e32 v106, v106
	v_exp_f32_e32 v107, v107
	v_exp_f32_e32 v80, v80
	v_exp_f32_e32 v81, v81
	v_exp_f32_e32 v82, v82
	v_exp_f32_e32 v83, v83
	v_exp_f32_e32 v84, v84
	v_mfma_f32_32x32x16_bf16 v[32:47], v[160:163], v[112:115], v[32:47]
	v_add_f32_e64 v112, v96, 0
	v_add_f32_e64 v113, v97, 0
	v_cvt_pk_bf16_f32 v96, v96, v97
	v_add_f32_e64 v112, v98, v112
	v_add_f32_e64 v113, v99, v113
	v_cvt_pk_bf16_f32 v97, v98, v99
	v_cvt_pk_bf16_f32 v98, v100, v101
	v_cvt_pk_bf16_f32 v99, v102, v103
	v_add_f32_e64 v112, v100, v112
	v_add_f32_e64 v113, v101, v113
	v_exp_f32_e32 v100, v108
	v_mfma_f32_32x32x16_bf16 v[64:79], v[188:191], v[96:99], v[64:79]
	v_exp_f32_e32 v101, v109
	v_add_f32_e64 v112, v102, v112
	v_add_f32_e64 v113, v103, v113
	v_exp_f32_e32 v102, v110
	v_exp_f32_e32 v103, v111
	v_add_f32_e64 v112, v104, v112
	v_add_f32_e64 v113, v105, v113
	v_exp_f32_e32 v85, v85
	v_add_f32_e64 v112, v106, v112
	v_add_f32_e64 v113, v107, v113
	v_mfma_f32_32x32x16_bf16 v[16:31], v[184:187], v[96:99], v[16:31]
	v_add_f32_e64 v108, v100, v112
	v_add_f32_e64 v109, v101, v113
	v_cvt_pk_bf16_f32 v98, v100, v101
	v_add_f32_e64 v96, v102, v108
	v_add_f32_e64 v97, v103, v109
	v_cvt_pk_bf16_f32 v99, v102, v103
	v_add_f32_e64 v108, v80, v96
	v_add_f32_e64 v109, v81, v97
	v_cvt_pk_bf16_f32 v96, v104, v105
	v_cvt_pk_bf16_f32 v97, v106, v107
	v_exp_f32_e32 v86, v86
	v_exp_f32_e32 v87, v87
	v_mfma_f32_32x32x16_bf16 v[64:79], v[180:183], v[96:99], v[64:79]
	v_add_f32_e64 v100, v82, v108
	v_add_f32_e64 v101, v83, v109
	v_exp_f32_e32 v88, v88
	v_add_f32_e64 v100, v84, v100
	v_add_f32_e64 v101, v85, v101
	v_exp_f32_e32 v89, v89
	v_cvt_pk_bf16_f32 v80, v80, v81
	v_cvt_pk_bf16_f32 v81, v82, v83
	v_cvt_pk_bf16_f32 v82, v84, v85
	v_mfma_f32_32x32x16_bf16 v[16:31], v[176:179], v[96:99], v[16:31]
	v_cvt_pk_bf16_f32 v83, v86, v87
	v_add_f32_e64 v96, v86, v100
	v_add_f32_e64 v97, v87, v101
	v_exp_f32_e32 v86, v90
	v_exp_f32_e32 v87, v91
	v_exp_f32_e32 v90, v92
	v_exp_f32_e32 v91, v93
	v_exp_f32_e32 v92, v94
	v_mfma_f32_32x32x16_bf16 v[64:79], v[172:175], v[80:83], v[64:79]
	v_exp_f32_e32 v93, v95
	s_addk_i32 s4, 0x4000
	v_add_f32_e64 v84, v88, v96
	v_add_f32_e64 v85, v89, v97
	s_cmp_lg_u32 s35, 2
	s_cselect_b32 s4, s4, 0
	s_add_i32 s4, s4, 32
	s_waitcnt vmcnt(0)
	v_mfma_f32_32x32x16_bf16 v[16:31], v[168:171], v[80:83], v[16:31]
	v_add_f32_e64 v80, v86, v84
	v_add_f32_e64 v81, v87, v85
	v_cvt_pk_bf16_f32 v82, v90, v91
	v_add_f32_e64 v80, v90, v80
	v_add_f32_e64 v81, v91, v81
	v_cvt_pk_bf16_f32 v83, v92, v93
	v_add_f32_e64 v168, v92, v80
	v_add_f32_e64 v169, v93, v81
	v_cvt_pk_bf16_f32 v80, v88, v89
	v_add_u32_e32 v88, s4, v217
	v_cvt_pk_bf16_f32 v81, v86, v87
	v_add_u32_e32 v174, v88, v219
	v_add_u32_e32 v175, v88, v218
	v_add_u32_e32 v176, v88, v216
	v_add_u32_e32 v177, v88, v215
	v_mfma_f32_32x32x16_bf16 v[64:79], v[164:167], v[80:83], v[64:79]
	s_barrier
; #define MFMA(a, b, c) __builtin_amdgcn_mfma_f32_32x32x16_bf16((a), (b), (c), 0, 0, 0)
; DI int otid() { int t = threadIdx.x; asm volatile("" : "+v"(t)); return t; }
; DI float xsum32(float x) { const unsigned u = __float_as_uint(x); const auto r2 = __builtin_amdgcn_permlane32_swap(u, u, false, false); return __uint_as_float(r2[0]) + __uint_as_float(r2[1]); }
; template <int KIND>
; DI void attn_unit(const Params& p, int l, int b, int head, int qt, int qcol, int kcol, int vfeat, int gcol, int mixcol,
;                   int t1, int n1, int t2, int n2, char* smem) {
;     ...
;         bf16x8 kf[8], vf[8];
;         if (active) {
; #pragma unroll
;             for (int s = 0; s < 4; ++s)
; #pragma unroll
;                 for (int t = 0; t < 2; ++t) kf[2 * s + t] = *(const bf16x8*)(sk + (32 * t + r) * 128 + (((2 * s + h) ^ xr) << 4));
;         }
;         __builtin_amdgcn_sched_barrier(0);
;         if (it + 2 < nt) { const int nx = (it + 2 < n1) ? t1 + it + 2 : t2 + (it + 2 - n1); KV_ISSUE(nx, sn); }
;         sc = (sc == 2) ? 0 : sc + 1; sn = (sn == 2) ? 0 : sn + 1;
;         __builtin_amdgcn_sched_barrier(0);
;         if (active) {
;     ...
;             if (KIND == 0) {
;                 f32x16 S0[2], S1[2];
; #pragma unroll
;                 for (int t = 0; t < 2; ++t) { S0[t] = MFMA(kf[t], qf[0], cz); S1[t] = MFMA(kf[4 + t], qf[2], cz); }
; #pragma unroll
;                 for (int t = 0; t < 2; ++t) { S0[t] = MFMA(kf[2 + t], qf[1], S0[t]); S1[t] = MFMA(kf[6 + t], qf[3], S1[t]); }
;                 LOAD_VF();
;                 softmax_tile(S0, l0);
;                 pv_tile(S0, O0, vf);
;                 softmax_tile(S1, l1);
;                 pv_tile(S1, O1, vf);
;     ...
;     l0 = xsum32(l0);
;     const float inv0 = 1.f / l0;
;     const int tid_e = otid();
;     const size_t qrow_e = (size_t)b * TPB + qt * 128 + 32 * (tid_e >> 6) + (tid_e & 31);
;     bf16_t* orow = p.hmix + ((size_t)(mixcol >> 5) * NTOK + qrow_e) * 32;
;     const bf16_t* grow = p.qkv + ((size_t)(gcol >> 6) * NTOK + qrow_e) * 64;
;     if (KIND == 0) {
;         l1 = xsum32(l1);
;         const float lam = p.lam[l];
;         const float inv1 = lam / l1;
	ds_read_b128 v[84:87], v174
	ds_read_b128 v[128:131], v174 offset:4096
	ds_read_b128 v[132:135], v175
	ds_read_b128 v[136:139], v175 offset:4096
	ds_read_b128 v[96:99], v176
	ds_read_b128 v[140:143], v176 offset:4096
	ds_read_b128 v[164:167], v177
	ds_read_b128 v[170:173], v177 offset:4096
	v_add_f32_e64 v116, v120, v116
	v_add_f32_e64 v117, v121, v117
	s_nop 0
	v_add_f32_e64 v116, v118, v116
	v_add_f32_e64 v117, v119, v117
	v_mfma_f32_32x32x16_bf16 v[16:31], v[160:163], v[80:83], v[16:31]
	v_add_f32_e64 v116, v122, v116
	v_add_f32_e64 v117, v123, v117
	v_add_f32_e64 v196, v124, v116
	v_add_f32_e64 v197, v125, v117
	s_waitcnt lgkmcnt(0)
	v_mfma_f32_32x32x16_bf16 v[112:127], v[84:87], v[152:155], v[0:15]
	v_mfma_f32_32x32x16_bf16 v[80:95], v[96:99], v[156:159], v[0:15]
	v_mfma_f32_32x32x16_bf16 v[96:111], v[128:131], v[152:155], v[0:15]
	v_mfma_f32_32x32x16_bf16 v[0:15], v[140:143], v[156:159], v[0:15]
	v_mfma_f32_32x32x16_bf16 v[112:127], v[132:135], v[144:147], v[112:127]
	v_mfma_f32_32x32x16_bf16 v[80:95], v[164:167], v[148:151], v[80:95]
	v_mfma_f32_32x32x16_bf16 v[96:111], v[136:139], v[144:147], v[96:111]
	v_mfma_f32_32x32x16_bf16 v[0:15], v[170:173], v[148:151], v[0:15]
	ds_read_b128 v[156:159], v174 offset:8192
	ds_read_b128 v[152:155], v174 offset:12288
	ds_read_b128 v[148:151], v175 offset:8192
	ds_read_b128 v[144:147], v175 offset:12288
	ds_read_b128 v[140:143], v176 offset:8192
	ds_read_b128 v[136:139], v176 offset:12288
	ds_read_b128 v[132:135], v177 offset:8192
	ds_read_b128 v[128:131], v177 offset:12288
	s_nop 0
	v_exp_f32_e32 v112, v112
	v_exp_f32_e32 v113, v113
	v_exp_f32_e32 v114, v114
	v_exp_f32_e32 v115, v115
	v_exp_f32_e32 v116, v116
	v_exp_f32_e32 v117, v117
	v_exp_f32_e32 v118, v118
	v_exp_f32_e32 v119, v119
	v_add_f32_e64 v160, v112, 0
	v_add_f32_e64 v161, v113, 0
	v_cvt_pk_bf16_f32 v112, v112, v113
	v_add_f32_e64 v160, v114, v160
	v_add_f32_e64 v161, v115, v161
	v_cvt_pk_bf16_f32 v113, v114, v115
	v_cvt_pk_bf16_f32 v114, v116, v117
	v_cvt_pk_bf16_f32 v115, v118, v119
	v_exp_f32_e32 v120, v120
	v_exp_f32_e32 v121, v121
	s_waitcnt lgkmcnt(0)
	v_mfma_f32_32x32x16_bf16 v[48:63], v[156:159], v[112:115], v[48:63]
	v_exp_f32_e32 v122, v122
	v_exp_f32_e32 v123, v123
	v_exp_f32_e32 v124, v124
	v_exp_f32_e32 v125, v125
	v_exp_f32_e32 v126, v126
	v_exp_f32_e32 v127, v127
	v_add_f32_e64 v160, v116, v160
	v_add_f32_e64 v161, v117, v161
	v_mfma_f32_32x32x16_bf16 v[32:47], v[152:155], v[112:115], v[32:47]
	v_add_f32_e64 v160, v118, v160
	v_add_f32_e64 v161, v119, v161
	v_exp_f32_e32 v118, v96
	v_add_f32_e64 v160, v120, v160
	v_add_f32_e64 v161, v121, v161
	v_exp_f32_e32 v119, v97
	v_add_f32_e64 v116, v122, v160
	v_add_f32_e64 v117, v123, v161
	v_exp_f32_e32 v160, v98
	v_exp_f32_e32 v161, v99
	v_cvt_pk_bf16_f32 v96, v120, v121
	v_cvt_pk_bf16_f32 v97, v122, v123
	v_cvt_pk_bf16_f32 v98, v124, v125
	v_cvt_pk_bf16_f32 v99, v126, v127
	v_add_f32_e64 v116, v124, v116
	v_add_f32_e64 v117, v125, v117
	v_exp_f32_e32 v100, v100
	v_mfma_f32_32x32x16_bf16 v[48:63], v[148:151], v[96:99], v[48:63]
	v_exp_f32_e32 v101, v101
	v_add_f32_e64 v116, v126, v116
	v_add_f32_e64 v117, v127, v117
	v_exp_f32_e32 v102, v102
	v_exp_f32_e32 v103, v103
	v_add_f32_e64 v112, v118, v116
	v_add_f32_e64 v113, v119, v117
	v_exp_f32_e32 v104, v104
	v_exp_f32_e32 v105, v105
	v_mfma_f32_32x32x16_bf16 v[32:47], v[144:147], v[96:99], v[32:47]
	v_add_f32_e64 v112, v160, v112
	v_add_f32_e64 v113, v161, v113
	v_exp_f32_e32 v106, v106
	v_exp_f32_e32 v107, v107
	v_add_f32_e64 v112, v100, v112
	v_add_f32_e64 v113, v101, v113
	v_exp_f32_e32 v108, v108
	v_add_f32_e64 v112, v102, v112
	v_add_f32_e64 v113, v103, v113
	v_cvt_pk_bf16_f32 v96, v118, v119
	v_cvt_pk_bf16_f32 v97, v160, v161
	v_cvt_pk_bf16_f32 v98, v100, v101
	v_cvt_pk_bf16_f32 v99, v102, v103
	v_exp_f32_e32 v109, v109
	v_exp_f32_e32 v100, v110
	v_mfma_f32_32x32x16_bf16 v[48:63], v[140:143], v[96:99], v[48:63]
	v_exp_f32_e32 v101, v111
	v_add_f32_e64 v102, v104, v112
	v_add_f32_e64 v103, v105, v113
	v_exp_f32_e32 v84, v84
	v_add_f32_e64 v102, v106, v102
	v_add_f32_e64 v103, v107, v103
	v_exp_f32_e32 v85, v85
	v_add_f32_e64 v102, v108, v102
	v_add_f32_e64 v103, v109, v103
	v_exp_f32_e32 v86, v86
	v_mfma_f32_32x32x16_bf16 v[32:47], v[136:139], v[96:99], v[32:47]
	v_cvt_pk_bf16_f32 v96, v104, v105
	v_exp_f32_e32 v104, v80
	v_exp_f32_e32 v105, v81
	v_cvt_pk_bf16_f32 v97, v106, v107
	v_exp_f32_e32 v106, v82
	v_exp_f32_e32 v107, v83
	v_exp_f32_e32 v87, v87
	v_add_f32_e64 v102, v100, v102
	v_add_f32_e64 v103, v101, v103
	v_add_f32_e64 v82, v104, 0
	v_add_f32_e64 v83, v105, 0
	v_exp_f32_e32 v88, v88
	v_exp_f32_e32 v89, v89
	v_mov_b32_e32 v110, v196
	v_mov_b32_e32 v111, v102
	v_mov_b32_e32 v102, v197
	v_add_f32_e64 v82, v106, v82
	v_add_f32_e64 v83, v107, v83
	v_exp_f32_e32 v90, v90
	v_exp_f32_e32 v91, v91
	v_cvt_pk_bf16_f32 v99, v100, v101
	v_add_f32_e64 v100, v110, v102
	v_add_f32_e64 v101, v111, v103
	v_add_f32_e64 v82, v84, v82
	v_add_f32_e64 v83, v85, v83
	v_exp_f32_e32 v92, v92
	v_exp_f32_e32 v93, v93
	s_add_u32 s7, s29, s7
	v_pk_add_f32 v[102:103], v[194:195], v[100:101] op_sel:[1,0] op_sel_hi:[0,1]
	v_add_f32_e64 v82, v86, v82
	v_add_f32_e64 v83, v87, v83
	s_addc_u32 s9, s9, 0
	s_add_i32 s8, s8, 0x36000
	s_lshl_b64 s[4:5], s[60:61], 2
	v_cvt_pk_bf16_f32 v98, v108, v109
	v_pk_add_f32 v[80:81], v[102:103], v[100:101] op_sel:[0,1] op_sel_hi:[1,0]
	v_add_f32_e64 v82, v88, v82
	v_add_f32_e64 v83, v89, v83
	s_add_u32 s4, s50, s4
	v_mfma_f32_32x32x16_bf16 v[48:63], v[132:135], v[96:99], v[48:63]
	v_mov_b32_e32 v81, v200
	s_addc_u32 s5, s51, s5
	v_cvt_pk_bf16_f32 v84, v84, v85
	v_cvt_pk_bf16_f32 v85, v86, v87
	v_exp_f32_e32 v94, v94
; DI int otid() { int t = threadIdx.x; asm volatile("" : "+v"(t)); return t; }
; DI float xsum32(float x) { const unsigned u = __float_as_uint(x); const auto r2 = __builtin_amdgcn_permlane32_swap(u, u, false, false); return __uint_as_float(r2[0]) + __uint_as_float(r2[1]); }
; template <int KIND>
; DI void attn_unit(const Params& p, int l, int b, int head, int qt, int qcol, int kcol, int vfeat, int gcol, int mixcol,
;                   int t1, int n1, int t2, int n2, char* smem) {
;     ...
;     l0 = xsum32(l0);
;     const float inv0 = 1.f / l0;
;     const int tid_e = otid();
;     const size_t qrow_e = (size_t)b * TPB + qt * 128 + 32 * (tid_e >> 6) + (tid_e & 31);
;     bf16_t* orow = p.hmix + ((size_t)(mixcol >> 5) * NTOK + qrow_e) * 32;
;     const bf16_t* grow = p.qkv + ((size_t)(gcol >> 6) * NTOK + qrow_e) * 64;
;     if (KIND == 0) {
;         l1 = xsum32(l1);
;         const float lam = p.lam[l];
;         const float inv1 = lam / l1;
;         float ss = 0.f;
; #pragma unroll
;         for (int t = 0; t < 2; ++t)
; #pragma unroll
;             for (int e = 0; e < 16; ++e) { const float o = O0[t][e] * inv0 - O1[t][e] * inv1; O0[t][e] = o; ss += o * o; }
;         ss = xsum32(ss);
;         const float rstd = rsqrtf(ss * (1.f / 64.f) + EPS) * p.lam[4 + l];
	v_exp_f32_e32 v95, v95
	v_mfma_f32_32x32x16_bf16 v[32:47], v[128:131], v[96:99], v[32:47]
	v_add_f32_e64 v96, v90, v82
	v_add_f32_e64 v97, v91, v83
	v_exp_f32_e32 v98, v0
	v_exp_f32_e32 v99, v1
	v_add_f32_e64 v0, v92, v96
	v_add_f32_e64 v1, v93, v97
	global_load_dword v96, v193, s[4:5]
	v_cvt_pk_bf16_f32 v82, v104, v105
	v_cvt_pk_bf16_f32 v83, v106, v107
	v_exp_f32_e32 v100, v2
	v_exp_f32_e32 v101, v3
	v_mfma_f32_32x32x16_bf16 v[64:79], v[156:159], v[82:85], v[64:79]
	v_exp_f32_e32 v86, v4
	v_exp_f32_e32 v87, v5
	v_cvt_pk_bf16_f32 v2, v88, v89
	v_cvt_pk_bf16_f32 v3, v90, v91
	v_cvt_pk_bf16_f32 v4, v92, v93
	v_cvt_pk_bf16_f32 v5, v94, v95
	v_add_f32_e64 v0, v94, v0
	v_add_f32_e64 v1, v95, v1
	v_mfma_f32_32x32x16_bf16 v[16:31], v[152:155], v[82:85], v[16:31]
	v_exp_f32_e32 v6, v6
	v_exp_f32_e32 v7, v7
	v_add_f32_e64 v0, v98, v0
	v_add_f32_e64 v1, v99, v1
	v_exp_f32_e32 v8, v8
	v_exp_f32_e32 v9, v9
	v_add_f32_e64 v0, v100, v0
	v_add_f32_e64 v1, v101, v1
	v_exp_f32_e32 v10, v10
	v_mfma_f32_32x32x16_bf16 v[64:79], v[148:151], v[2:5], v[64:79]
	v_exp_f32_e32 v11, v11
	v_add_f32_e64 v82, v86, v0
	v_add_f32_e64 v83, v87, v1
	v_exp_f32_e32 v12, v12
	v_exp_f32_e32 v13, v13
	v_add_f32_e64 v82, v6, v82
	v_add_f32_e64 v83, v7, v83
	v_ashrrev_i32_e32 v0, 1, v81
	v_and_b32_e32 v0, 0xffffffe0, v0
	v_mfma_f32_32x32x16_bf16 v[16:31], v[144:147], v[2:5], v[16:31]
	v_cvt_pk_bf16_f32 v5, v6, v7
	v_exp_f32_e32 v6, v14
	v_exp_f32_e32 v7, v15
	v_add_f32_e64 v14, v8, v82
	v_add_f32_e64 v15, v9, v83
	v_cvt_pk_bf16_f32 v2, v98, v99
	v_add_f32_e64 v14, v10, v14
	v_add_f32_e64 v15, v11, v15
	v_cvt_pk_bf16_f32 v3, v100, v101
	v_cvt_pk_bf16_f32 v4, v86, v87
	v_add_f32_e64 v14, v12, v14
	v_add_f32_e64 v15, v13, v15
	v_ashrrev_i32_e32 v1, 31, v0
	v_mfma_f32_32x32x16_bf16 v[64:79], v[140:143], v[2:5], v[64:79]
	v_add_f32_e64 v14, v6, v14
	v_add_f32_e64 v15, v7, v15
	v_and_or_b32 v84, v81, 31, s7
	v_mov_b32_e32 v85, s9
	v_lshl_add_u64 v[84:85], v[84:85], 0, v[0:1]
	s_mov_b32 s9, s75
	v_lshl_add_u64 v[0:1], v[84:85], 0, s[8:9]
	v_mov_b32_e32 v82, v168
	v_mfma_f32_32x32x16_bf16 v[16:31], v[136:139], v[2:5], v[16:31]
	v_cvt_pk_bf16_f32 v5, v6, v7
	v_mov_b32_e32 v6, v80
	s_nop 1
	v_permlane32_swap_b32_e32 v80, v6
	v_cvt_pk_bf16_f32 v2, v8, v9
	v_add_f32_e32 v8, v80, v6
	v_div_scale_f32 v9, s[8:9], v8, v8, 1.0
	v_cvt_pk_bf16_f32 v3, v10, v11
	v_rcp_f32_e32 v10, v9
	v_cvt_pk_bf16_f32 v4, v12, v13
	v_mov_b32_e32 v83, v14
	v_mov_b32_e32 v14, v169
	v_mfma_f32_32x32x16_bf16 v[64:79], v[132:135], v[2:5], v[64:79]
	v_add_f32_e64 v14, v82, v14
	v_add_f32_e64 v15, v83, v15
	global_load_dword v80, v193, s[4:5] offset:16
	v_add_f32_e64 v6, v194, v14
	v_add_f32_e64 v7, v195, v15
	v_lshlrev_b64 v[0:1], 7, v[0:1]
	v_pk_add_f32 v[6:7], v[6:7], v[14:15] op_sel:[0,1] op_sel_hi:[1,0]
	v_lshl_add_u64 v[0:1], s[40:41], 0, v[0:1]
	v_lshlrev_b32_e32 v88, 3, v214
	v_mfma_f32_32x32x16_bf16 v[16:31], v[128:131], v[2:5], v[16:31]
	v_fma_f32 v2, -v9, v10, 1.0
	v_fmac_f32_e32 v10, v2, v10
	v_div_scale_f32 v2, vcc, 1.0, v8, 1.0
	v_mul_f32_e32 v3, v2, v10
	v_fma_f32 v4, -v9, v3, v2
	v_fmac_f32_e32 v3, v4, v10
	v_fma_f32 v2, -v9, v3, v2
	v_div_fmas_f32 v2, v2, v10, v3
	v_div_fixup_f32 v8, v2, v8, 1.0
	v_mov_b32_e32 v2, v6
	s_nop 1
	v_permlane32_swap_b32_e32 v6, v2
	v_add_f32_e32 v4, v6, v2
	s_waitcnt vmcnt(0)
	v_div_scale_f32 v5, s[4:5], v4, v4, v96
	v_rcp_f32_e32 v6, v5
	v_mov_b32_e32 v89, v193
	v_lshl_add_u64 v[0:1], v[0:1], 0, v[88:89]
	s_mul_i32 s6, s6, 0x9000
	v_fma_f32 v7, -v5, v6, 1.0
	s_mov_b32 s7, s75
	v_fmac_f32_e32 v6, v7, v6
	v_div_scale_f32 v7, vcc, v96, v4, v96
	global_load_dwordx2 v[90:91], v[0:1], off
	v_lshl_add_u64 v[2:3], v[84:85], 0, s[6:7]
	v_mul_f32_e32 v9, v7, v6
	s_load_dwordx2 s[4:5], s[0:1], 0xb8
	s_load_dwordx2 s[6:7], s[0:1], 0x78
	v_fma_f32 v10, -v5, v9, v7
	v_fmac_f32_e32 v9, v10, v6
	v_fma_f32 v5, -v5, v9, v7
	v_lshlrev_b64 v[2:3], 6, v[2:3]
	v_div_fmas_f32 v5, v5, v6, v9
	v_div_fixup_f32 v10, v5, v4, v96
	s_waitcnt lgkmcnt(0)
	v_lshl_add_u64 v[2:3], s[4:5], 0, v[2:3]
	s_add_u32 s4, s6, s46
	s_addc_u32 s5, s7, s47
	v_pk_mul_f32 v[4:5], v[66:67], v[10:11] op_sel_hi:[1,0]
	v_pk_mul_f32 v[16:17], v[16:17], v[10:11] op_sel_hi:[1,0]
	v_pk_fma_f32 v[14:15], v[50:51], v[8:9], v[4:5] op_sel_hi:[1,0,1] neg_lo:[0,0,1] neg_hi:[0,0,1]
	global_load_dwordx4 v[4:7], v192, s[4:5]
	v_pk_mul_f32 v[50:51], v[64:65], v[10:11] op_sel_hi:[1,0]
	v_mul_f32_e32 v64, v15, v15
	v_pk_fma_f32 v[48:49], v[48:49], v[8:9], v[50:51] op_sel_hi:[1,0,1] neg_lo:[0,0,1] neg_hi:[0,0,1]
	v_pk_mul_f32 v[18:19], v[18:19], v[10:11] op_sel_hi:[1,0]
	v_mul_f32_e32 v50, v49, v49
	v_pk_fma_f32 v[50:51], v[48:49], v[48:49], v[50:51] op_sel_hi:[1,1,0]
	v_pk_fma_f32 v[16:17], v[32:33], v[8:9], v[16:17] op_sel_hi:[1,0,1] neg_lo:[0,0,1] neg_hi:[0,0,1]
	v_pk_fma_f32 v[50:51], v[14:15], v[14:15], v[50:51]
	v_pk_fma_f32 v[18:19], v[34:35], v[8:9], v[18:19] op_sel_hi:[1,0,1] neg_lo:[0,0,1] neg_hi:[0,0,1]
	v_pk_add_f32 v[50:51], v[64:65], v[50:51] op_sel_hi:[0,1]
	v_pk_mul_f32 v[64:65], v[70:71], v[10:11] op_sel_hi:[1,0]
	v_mul_f32_e32 v34, v17, v17
	v_pk_fma_f32 v[54:55], v[54:55], v[8:9], v[64:65] op_sel_hi:[1,0,1] neg_lo:[0,0,1] neg_hi:[0,0,1]
	v_pk_mul_f32 v[64:65], v[68:69], v[10:11] op_sel_hi:[1,0]
	v_pk_mul_f32 v[20:21], v[20:21], v[10:11] op_sel_hi:[1,0]
	v_pk_fma_f32 v[52:53], v[52:53], v[8:9], v[64:65] op_sel_hi:[1,0,1] neg_lo:[0,0,1] neg_hi:[0,0,1]
	v_pk_fma_f32 v[20:21], v[36:37], v[8:9], v[20:21] op_sel_hi:[1,0,1] neg_lo:[0,0,1] neg_hi:[0,0,1]
	v_pk_fma_f32 v[50:51], v[52:53], v[52:53], v[50:51]
	v_mul_f32_e32 v64, v53, v53
	v_pk_add_f32 v[50:51], v[64:65], v[50:51] op_sel_hi:[0,1]
	v_pk_fma_f32 v[50:51], v[54:55], v[54:55], v[50:51]
; DI unsigned pk2(float a, float b) { f2_t v = {a, b}; bf2_t r = __builtin_convertvector(v, bf2_t); return __builtin_bit_cast(unsigned, r); }
; DI float bf2f(bf16_t v) { return __uint_as_float(((unsigned)v) << 16); }
; DI float xsum32(float x) { const unsigned u = __float_as_uint(x); const auto r2 = __builtin_amdgcn_permlane32_swap(u, u, false, false); return __uint_as_float(r2[0]) + __uint_as_float(r2[1]); }
; template <int KIND>
; DI void attn_unit(const Params& p, int l, int b, int head, int qt, int qcol, int kcol, int vfeat, int gcol, int mixcol,
;                   int t1, int n1, int t2, int n2, char* smem) {
;     ...
;         float ss = 0.f;
; #pragma unroll
;         for (int t = 0; t < 2; ++t)
; #pragma unroll
;             for (int e = 0; e < 16; ++e) { const float o = O0[t][e] * inv0 - O1[t][e] * inv1; O0[t][e] = o; ss += o * o; }
;         ss = xsum32(ss);
;         const float rstd = rsqrtf(ss * (1.f / 64.f) + EPS) * p.lam[4 + l];
;         const float* sw = p.subln + l * 64;
; #pragma unroll
;         for (int t = 0; t < 2; ++t)
; #pragma unroll
;             for (int q = 0; q < 4; ++q) {
;                 const int f = 32 * t + 8 * q + 4 * h;
;                 const float4 w4 = *(const float4*)(sw + f);
;                 const uint2 gg = *(const uint2*)(grow + f);
;                 const float g0 = bf2f((bf16_t)(gg.x & 0xffff)), g1 = bf2f((bf16_t)(gg.x >> 16)), g2 = bf2f((bf16_t)(gg.y & 0xffff)), g3 = bf2f((bf16_t)(gg.y >> 16));
;                 uint2 o;
;                 o.x = pk2(O0[t][4 * q + 0] * rstd * w4.x * g0, O0[t][4 * q + 1] * rstd * w4.y * g1);
;                 o.y = pk2(O0[t][4 * q + 2] * rstd * w4.z * g2, O0[t][4 * q + 3] * rstd * w4.w * g3);
;                 *(uint2*)(orow + (size_t)t * NTOK * 32 + 8 * q + 4 * h) = o;
;             }
	v_mul_f32_e32 v64, v55, v55
	v_pk_add_f32 v[50:51], v[64:65], v[50:51] op_sel_hi:[0,1]
	v_pk_mul_f32 v[64:65], v[74:75], v[10:11] op_sel_hi:[1,0]
	v_pk_mul_f32 v[22:23], v[22:23], v[10:11] op_sel_hi:[1,0]
	v_pk_fma_f32 v[58:59], v[58:59], v[8:9], v[64:65] op_sel_hi:[1,0,1] neg_lo:[0,0,1] neg_hi:[0,0,1]
	v_pk_mul_f32 v[64:65], v[72:73], v[10:11] op_sel_hi:[1,0]
	v_pk_fma_f32 v[22:23], v[38:39], v[8:9], v[22:23] op_sel_hi:[1,0,1] neg_lo:[0,0,1] neg_hi:[0,0,1]
	v_pk_fma_f32 v[56:57], v[56:57], v[8:9], v[64:65] op_sel_hi:[1,0,1] neg_lo:[0,0,1] neg_hi:[0,0,1]
	v_pk_mul_f32 v[24:25], v[24:25], v[10:11] op_sel_hi:[1,0]
	v_pk_fma_f32 v[50:51], v[56:57], v[56:57], v[50:51]
	v_mul_f32_e32 v64, v57, v57
	v_pk_add_f32 v[50:51], v[64:65], v[50:51] op_sel_hi:[0,1]
	v_pk_fma_f32 v[50:51], v[58:59], v[58:59], v[50:51]
	v_mul_f32_e32 v64, v59, v59
	v_pk_add_f32 v[50:51], v[64:65], v[50:51] op_sel_hi:[0,1]
	v_pk_mul_f32 v[64:65], v[78:79], v[10:11] op_sel_hi:[1,0]
	v_pk_fma_f32 v[24:25], v[40:41], v[8:9], v[24:25] op_sel_hi:[1,0,1] neg_lo:[0,0,1] neg_hi:[0,0,1]
	v_pk_fma_f32 v[62:63], v[62:63], v[8:9], v[64:65] op_sel_hi:[1,0,1] neg_lo:[0,0,1] neg_hi:[0,0,1]
	v_pk_mul_f32 v[64:65], v[76:77], v[10:11] op_sel_hi:[1,0]
	v_pk_mul_f32 v[26:27], v[26:27], v[10:11] op_sel_hi:[1,0]
	v_pk_fma_f32 v[60:61], v[60:61], v[8:9], v[64:65] op_sel_hi:[1,0,1] neg_lo:[0,0,1] neg_hi:[0,0,1]
	v_pk_fma_f32 v[26:27], v[42:43], v[8:9], v[26:27] op_sel_hi:[1,0,1] neg_lo:[0,0,1] neg_hi:[0,0,1]
	v_pk_fma_f32 v[50:51], v[60:61], v[60:61], v[50:51]
	v_mul_f32_e32 v64, v61, v61
	v_pk_add_f32 v[50:51], v[64:65], v[50:51] op_sel_hi:[0,1]
	v_pk_fma_f32 v[50:51], v[62:63], v[62:63], v[50:51]
	v_mul_f32_e32 v64, v63, v63
	v_pk_add_f32 v[50:51], v[64:65], v[50:51] op_sel_hi:[0,1]
	v_pk_fma_f32 v[32:33], v[16:17], v[16:17], v[50:51]
	v_pk_mul_f32 v[30:31], v[30:31], v[10:11] op_sel_hi:[1,0]
	v_pk_add_f32 v[32:33], v[34:35], v[32:33] op_sel_hi:[0,1]
	v_pk_fma_f32 v[32:33], v[18:19], v[18:19], v[32:33]
	v_mul_f32_e32 v34, v19, v19
	v_pk_add_f32 v[32:33], v[34:35], v[32:33] op_sel_hi:[0,1]
	v_pk_fma_f32 v[32:33], v[20:21], v[20:21], v[32:33]
	v_mul_f32_e32 v34, v21, v21
	v_pk_add_f32 v[32:33], v[34:35], v[32:33] op_sel_hi:[0,1]
	v_pk_fma_f32 v[32:33], v[22:23], v[22:23], v[32:33]
	v_mul_f32_e32 v34, v23, v23
	v_pk_add_f32 v[32:33], v[34:35], v[32:33] op_sel_hi:[0,1]
	v_pk_fma_f32 v[32:33], v[24:25], v[24:25], v[32:33]
	v_mul_f32_e32 v34, v25, v25
	v_pk_add_f32 v[32:33], v[34:35], v[32:33] op_sel_hi:[0,1]
	v_pk_fma_f32 v[32:33], v[26:27], v[26:27], v[32:33]
	v_mul_f32_e32 v34, v27, v27
	v_pk_mul_f32 v[10:11], v[28:29], v[10:11] op_sel_hi:[1,0]
	v_pk_add_f32 v[32:33], v[34:35], v[32:33] op_sel_hi:[0,1]
	v_pk_fma_f32 v[30:31], v[46:47], v[8:9], v[30:31] op_sel_hi:[1,0,1] neg_lo:[0,0,1] neg_hi:[0,0,1]
	v_pk_fma_f32 v[8:9], v[44:45], v[8:9], v[10:11] op_sel_hi:[1,0,1] neg_lo:[0,0,1] neg_hi:[0,0,1]
	s_waitcnt vmcnt(1)
	v_lshlrev_b32_e32 v12, 16, v90
	v_pk_fma_f32 v[10:11], v[8:9], v[8:9], v[32:33]
	v_mul_f32_e32 v28, v9, v9
	v_pk_add_f32 v[10:11], v[28:29], v[10:11] op_sel_hi:[0,1]
	v_pk_fma_f32 v[10:11], v[30:31], v[30:31], v[10:11]
	v_mul_f32_e32 v28, v31, v31
	v_pk_add_f32 v[10:11], v[28:29], v[10:11] op_sel_hi:[0,1]
	v_mov_b32_e32 v11, v10
	s_nop 1
	v_permlane32_swap_b32_e32 v10, v11
	v_add_f32_e32 v10, v10, v11
	v_fmamk_f32 v10, v10, 0x3c800000, v201
	v_mul_f32_e32 v11, 0x4b800000, v10
	v_cmp_gt_f32_e32 vcc, s87, v10
	v_and_b32_e32 v13, 0xffff0000, v90
	v_lshl_add_u64 v[2:3], v[2:3], 0, v[88:89]
	v_cndmask_b32_e32 v10, v10, v11, vcc
	v_rsq_f32_e32 v28, v10
	v_lshlrev_b32_e32 v10, 16, v91
	v_and_b32_e32 v11, 0xffff0000, v91
	s_mov_b32 s6, 0x120000
	v_mul_f32_e32 v29, 0x45800000, v28
	v_cndmask_b32_e32 v28, v28, v29, vcc
	v_mul_f32_e32 v28, v80, v28
	v_pk_mul_f32 v[32:33], v[48:49], v[28:29] op_sel_hi:[1,0]
	s_waitcnt vmcnt(0)
	v_pk_mul_f32 v[4:5], v[4:5], v[32:33]
	s_nop 0
	v_pk_mul_f32 v[4:5], v[4:5], v[12:13]
	v_pk_mul_f32 v[12:13], v[14:15], v[28:29] op_sel_hi:[1,0]
	v_cvt_pk_bf16_f32 v4, v4, v5
	v_pk_mul_f32 v[6:7], v[6:7], v[12:13]
	v_pk_mul_f32 v[14:15], v[52:53], v[28:29] op_sel_hi:[1,0]
	v_pk_mul_f32 v[6:7], v[6:7], v[10:11]
	s_nop 0
	v_cvt_pk_bf16_f32 v5, v6, v7
	global_store_dwordx2 v[2:3], v[4:5], off
	global_load_dwordx2 v[10:11], v[0:1], off offset:16
	s_nop 0
	global_load_dwordx4 v[4:7], v192, s[4:5] offset:32
	s_waitcnt vmcnt(1)
	v_lshlrev_b32_e32 v12, 16, v10
	v_and_b32_e32 v13, 0xffff0000, v10
	s_waitcnt vmcnt(0)
; DI unsigned pk2(float a, float b) { f2_t v = {a, b}; bf2_t r = __builtin_convertvector(v, bf2_t); return __builtin_bit_cast(unsigned, r); }
; DI float bf2f(bf16_t v) { return __uint_as_float(((unsigned)v) << 16); }
; template <int KIND>
; DI void attn_unit(const Params& p, int l, int b, int head, int qt, int qcol, int kcol, int vfeat, int gcol, int mixcol,
;                   int t1, int n1, int t2, int n2, char* smem) {
;     ...
;         for (int t = 0; t < 2; ++t)
; #pragma unroll
;             for (int q = 0; q < 4; ++q) {
;                 const int f = 32 * t + 8 * q + 4 * h;
;                 const float4 w4 = *(const float4*)(sw + f);
;                 const uint2 gg = *(const uint2*)(grow + f);
;                 const float g0 = bf2f((bf16_t)(gg.x & 0xffff)), g1 = bf2f((bf16_t)(gg.x >> 16)), g2 = bf2f((bf16_t)(gg.y & 0xffff)), g3 = bf2f((bf16_t)(gg.y >> 16));
;                 uint2 o;
;                 o.x = pk2(O0[t][4 * q + 0] * rstd * w4.x * g0, O0[t][4 * q + 1] * rstd * w4.y * g1);
;                 o.y = pk2(O0[t][4 * q + 2] * rstd * w4.z * g2, O0[t][4 * q + 3] * rstd * w4.w * g3);
;                 *(uint2*)(orow + (size_t)t * NTOK * 32 + 8 * q + 4 * h) = o;
;             }
	v_pk_mul_f32 v[4:5], v[4:5], v[14:15]
	v_lshlrev_b32_e32 v10, 16, v11
	v_pk_mul_f32 v[4:5], v[4:5], v[12:13]
	v_pk_mul_f32 v[12:13], v[54:55], v[28:29] op_sel_hi:[1,0]
	v_and_b32_e32 v11, 0xffff0000, v11
	v_pk_mul_f32 v[6:7], v[12:13], v[6:7]
	v_cvt_pk_bf16_f32 v4, v4, v5
	v_pk_mul_f32 v[6:7], v[6:7], v[10:11]
	v_pk_mul_f32 v[14:15], v[56:57], v[28:29] op_sel_hi:[1,0]
	v_cvt_pk_bf16_f32 v5, v6, v7
	global_store_dwordx2 v[2:3], v[4:5], off offset:16
	global_load_dwordx2 v[10:11], v[0:1], off offset:32
	s_nop 0
	global_load_dwordx4 v[4:7], v192, s[4:5] offset:64
	s_waitcnt vmcnt(1)
	v_lshlrev_b32_e32 v12, 16, v10
	v_and_b32_e32 v13, 0xffff0000, v10
	s_waitcnt vmcnt(0)
	v_pk_mul_f32 v[4:5], v[14:15], v[4:5]
	v_lshlrev_b32_e32 v10, 16, v11
	v_pk_mul_f32 v[4:5], v[4:5], v[12:13]
	v_pk_mul_f32 v[12:13], v[58:59], v[28:29] op_sel_hi:[1,0]
	v_and_b32_e32 v11, 0xffff0000, v11
	v_pk_mul_f32 v[6:7], v[12:13], v[6:7]
	v_cvt_pk_bf16_f32 v4, v4, v5
	v_pk_mul_f32 v[6:7], v[6:7], v[10:11]
	v_pk_mul_f32 v[12:13], v[60:61], v[28:29] op_sel_hi:[1,0]
	v_cvt_pk_bf16_f32 v5, v6, v7
	global_store_dwordx2 v[2:3], v[4:5], off offset:32
	global_load_dwordx2 v[10:11], v[0:1], off offset:48
	s_nop 0
	global_load_dwordx4 v[4:7], v192, s[4:5] offset:96
	v_pk_mul_f32 v[14:15], v[62:63], v[28:29] op_sel_hi:[1,0]
	s_waitcnt vmcnt(1)
	v_lshlrev_b32_e32 v32, 16, v10
	v_and_b32_e32 v33, 0xffff0000, v10
	v_lshlrev_b32_e32 v10, 16, v11
	v_and_b32_e32 v11, 0xffff0000, v11
	s_waitcnt vmcnt(0)
	v_pk_mul_f32 v[4:5], v[12:13], v[4:5]
	v_pk_mul_f32 v[6:7], v[14:15], v[6:7]
	v_pk_mul_f32 v[4:5], v[4:5], v[32:33]
	v_pk_mul_f32 v[6:7], v[6:7], v[10:11]
	v_cvt_pk_bf16_f32 v4, v4, v5
	v_cvt_pk_bf16_f32 v5, v6, v7
	global_store_dwordx2 v[2:3], v[4:5], off offset:48
	global_load_dwordx2 v[10:11], v[0:1], off offset:64
	s_nop 0
	global_load_dwordx4 v[4:7], v192, s[4:5] offset:128
	v_add_co_u32_e32 v12, vcc, s6, v2
	v_pk_mul_f32 v[14:15], v[18:19], v[28:29] op_sel_hi:[1,0]
	s_nop 0
	v_addc_co_u32_e32 v13, vcc, 0, v3, vcc
	v_pk_mul_f32 v[2:3], v[16:17], v[28:29] op_sel_hi:[1,0]
	s_waitcnt vmcnt(1)
	v_lshlrev_b32_e32 v16, 16, v10
	v_and_b32_e32 v17, 0xffff0000, v10
	v_lshlrev_b32_e32 v10, 16, v11
	v_and_b32_e32 v11, 0xffff0000, v11
	s_waitcnt vmcnt(0)
	v_pk_mul_f32 v[2:3], v[2:3], v[4:5]
	v_pk_mul_f32 v[4:5], v[14:15], v[6:7]
	v_pk_mul_f32 v[2:3], v[2:3], v[16:17]
	v_pk_mul_f32 v[4:5], v[4:5], v[10:11]
	v_cvt_pk_bf16_f32 v2, v2, v3
	v_cvt_pk_bf16_f32 v3, v4, v5
	global_store_dwordx2 v[12:13], v[2:3], off
	global_load_dwordx2 v[6:7], v[0:1], off offset:80
	s_nop 0
	global_load_dwordx4 v[2:5], v192, s[4:5] offset:160
	v_pk_mul_f32 v[10:11], v[20:21], v[28:29] op_sel_hi:[1,0]
	v_pk_mul_f32 v[14:15], v[22:23], v[28:29] op_sel_hi:[1,0]
	s_waitcnt vmcnt(1)
	v_lshlrev_b32_e32 v16, 16, v6
	v_and_b32_e32 v17, 0xffff0000, v6
	v_lshlrev_b32_e32 v6, 16, v7
	v_and_b32_e32 v7, 0xffff0000, v7
	s_waitcnt vmcnt(0)
	v_pk_mul_f32 v[2:3], v[10:11], v[2:3]
	v_pk_mul_f32 v[4:5], v[14:15], v[4:5]
	v_pk_mul_f32 v[2:3], v[2:3], v[16:17]
	v_pk_mul_f32 v[4:5], v[4:5], v[6:7]
	v_cvt_pk_bf16_f32 v2, v2, v3
	v_cvt_pk_bf16_f32 v3, v4, v5
	global_store_dwordx2 v[12:13], v[2:3], off offset:16
	global_load_dwordx2 v[6:7], v[0:1], off offset:96
	s_nop 0
	global_load_dwordx4 v[2:5], v192, s[4:5] offset:192
	v_pk_mul_f32 v[10:11], v[24:25], v[28:29] op_sel_hi:[1,0]
	v_pk_mul_f32 v[14:15], v[26:27], v[28:29] op_sel_hi:[1,0]
	s_waitcnt vmcnt(1)
	v_lshlrev_b32_e32 v16, 16, v6
	v_and_b32_e32 v17, 0xffff0000, v6
	v_lshlrev_b32_e32 v6, 16, v7
	v_and_b32_e32 v7, 0xffff0000, v7
	s_waitcnt vmcnt(0)
	v_pk_mul_f32 v[2:3], v[10:11], v[2:3]
	v_pk_mul_f32 v[4:5], v[14:15], v[4:5]
	v_pk_mul_f32 v[2:3], v[2:3], v[16:17]
	v_pk_mul_f32 v[4:5], v[4:5], v[6:7]
	v_cvt_pk_bf16_f32 v2, v2, v3
	v_cvt_pk_bf16_f32 v3, v4, v5
	global_store_dwordx2 v[12:13], v[2:3], off offset:32
	global_load_dwordx2 v[4:5], v[0:1], off offset:112
	s_nop 0
	global_load_dwordx4 v[0:3], v192, s[4:5] offset:224
	v_pk_mul_f32 v[6:7], v[8:9], v[28:29] op_sel_hi:[1,0]
	v_pk_mul_f32 v[8:9], v[30:31], v[28:29] op_sel_hi:[1,0]
	s_mov_b64 s[4:5], 0
	s_waitcnt vmcnt(1)
	v_lshlrev_b32_e32 v10, 16, v4
	v_and_b32_e32 v11, 0xffff0000, v4
	v_lshlrev_b32_e32 v4, 16, v5
	v_and_b32_e32 v5, 0xffff0000, v5
	s_waitcnt vmcnt(0)
	v_pk_mul_f32 v[0:1], v[6:7], v[0:1]
	v_pk_mul_f32 v[2:3], v[8:9], v[2:3]
	v_pk_mul_f32 v[0:1], v[0:1], v[10:11]
	v_pk_mul_f32 v[2:3], v[2:3], v[4:5]
	v_cvt_pk_bf16_f32 v0, v0, v1
	v_cvt_pk_bf16_f32 v1, v2, v3
	global_store_dwordx2 v[12:13], v[0:1], off offset:48
	s_branch .LBB0_71
